# C5 + attention: rel-pos-bias lookups of tiles 1..7 prefetched in one LDS burst (no per-element branch+wait)
# baseline (speedup 1.0000x reference)
; __device__ __forceinline__ f32x4 mfma16(bf16x8 a, bf16x8 b, f32x4 c) { return __builtin_amdgcn_mfma_f32_16x16x32_bf16(a, b, c, 0, 0, 0); }
; __device__ __forceinline__ void phase_attn(const Args& a, unsigned char* smem, int tid, int lane, int wave, bf16_t* Yout) {
;     ...
; #pragma unroll
;             for (int bt = 0; bt < 4; ++bt) {
;                 ATT_KLOAD(bt, 0);
;                 asm volatile("" ::: "memory");
; #pragma unroll
;                 for (int ii = 0; ii < 2; ++ii) {
;                     const int i = bt * 2 + ii;
;                     const float* rp = rpb_s + (rs + i - r + 7) * 31;
; #pragma unroll
;                     for (int hf = 0; hf < 2; ++hf) {
;                         f32x4 s = {0.f, 0.f, 0.f, 0.f};
;                         s = mfma16(kbuf[0][(ii * 2 + hf) * 2], qf0, s); s = mfma16(kbuf[0][(ii * 2 + hf) * 2 + 1], qf1, s);
; #pragma unroll
;                         for (int e = 0; e < 4; ++e) { const int kc = kc0 + 8 * g + 4 * hf + e; const bool ok = (kc >= cs) && (kc < cs + 16);
;                             const int dc = min(max(kc - qc + 15, 0), 30);
;                             s[e] = ok ? s[e] * 0.125f + rp[dc] : -1e30f; }
;                         st[i * 2 + hf] = s;
.LBB0_351:
	s_or_b64 exec, exec, s[38:39]
	v_add_u32_e32 v52, 15, v38
	v_min_u32_e32 v52, 30, v52
	v_lshl_add_u32 v52, v52, 2, s1
	v_add_u32_e32 v53, 15, v39
	v_min_u32_e32 v53, 30, v53
	v_lshl_add_u32 v53, v53, 2, s1
	v_add_u32_e32 v54, 15, v40
	v_min_u32_e32 v54, 30, v54
	v_lshl_add_u32 v54, v54, 2, s1
	v_add_u32_e32 v55, 15, v41
	v_min_u32_e32 v55, 30, v55
	v_lshl_add_u32 v55, v55, 2, s1
	v_add_u32_e32 v56, 15, v42
	v_min_u32_e32 v56, 30, v56
	v_lshl_add_u32 v56, v56, 2, s1
	v_add_u32_e32 v57, 15, v43
	v_min_u32_e32 v57, 30, v57
	v_lshl_add_u32 v57, v57, 2, s1
	v_add_u32_e32 v58, 15, v44
	v_min_u32_e32 v58, 30, v58
	v_lshl_add_u32 v58, v58, 2, s1
	v_add_u32_e32 v59, 15, v45
	v_min_u32_e32 v59, 30, v59
	v_lshl_add_u32 v59, v59, 2, s1
	ds_read_b32 v60, v52 offset:992
	ds_read_b32 v61, v53 offset:992
	ds_read_b32 v62, v54 offset:992
	ds_read_b32 v63, v55 offset:992
	ds_read_b32 v64, v56 offset:992
	ds_read_b32 v65, v57 offset:992
	ds_read_b32 v66, v58 offset:992
	ds_read_b32 v67, v59 offset:992
	ds_read_b32 v184, v52 offset:1116
	ds_read_b32 v185, v53 offset:1116
	ds_read_b32 v186, v54 offset:1116
	ds_read_b32 v187, v55 offset:1116
	ds_read_b32 v188, v56 offset:1116
	ds_read_b32 v189, v57 offset:1116
	ds_read_b32 v190, v58 offset:1116
	ds_read_b32 v191, v59 offset:1116
	ds_read_b32 v192, v52 offset:1240
	ds_read_b32 v193, v53 offset:1240
	ds_read_b32 v194, v54 offset:1240
	ds_read_b32 v195, v55 offset:1240
	ds_read_b32 v196, v56 offset:1240
	ds_read_b32 v197, v57 offset:1240
	ds_read_b32 v198, v58 offset:1240
	ds_read_b32 v199, v59 offset:1240
	ds_read_b32 v200, v52 offset:1364
	ds_read_b32 v201, v53 offset:1364
	ds_read_b32 v202, v54 offset:1364
	ds_read_b32 v203, v55 offset:1364
	ds_read_b32 v204, v56 offset:1364
	ds_read_b32 v205, v57 offset:1364
	ds_read_b32 v206, v58 offset:1364
	ds_read_b32 v207, v59 offset:1364
	ds_read_b32 v208, v52 offset:1488
	ds_read_b32 v209, v53 offset:1488
	ds_read_b32 v210, v54 offset:1488
	ds_read_b32 v211, v55 offset:1488
	ds_read_b32 v212, v56 offset:1488
	ds_read_b32 v213, v57 offset:1488
	ds_read_b32 v214, v58 offset:1488
	ds_read_b32 v215, v59 offset:1488
	ds_read_b32 v227, v52 offset:1612
	ds_read_b32 v228, v53 offset:1612
	ds_read_b32 v229, v54 offset:1612
	ds_read_b32 v230, v55 offset:1612
	ds_read_b32 v231, v56 offset:1612
	ds_read_b32 v232, v57 offset:1612
	ds_read_b32 v233, v58 offset:1612
	ds_read_b32 v234, v59 offset:1612
	ds_read_b32 v235, v52 offset:1736
	ds_read_b32 v236, v53 offset:1736
	ds_read_b32 v237, v54 offset:1736
	ds_read_b32 v238, v55 offset:1736
	ds_read_b32 v239, v56 offset:1736
	ds_read_b32 v240, v57 offset:1736
	ds_read_b32 v241, v58 offset:1736
	s_waitcnt vmcnt(3)
	v_mfma_f32_16x16x32_bf16 v[20:23], v[20:23], v[4:7], 0
	v_mov_b32_e32 v76, 0xf149f2ca
	v_mov_b32_e32 v77, 0xf149f2ca
	s_waitcnt vmcnt(2)
	v_mfma_f32_16x16x32_bf16 v[16:19], v[16:19], v[0:3], v[20:23]
	s_waitcnt lgkmcnt(0)
	s_and_saveexec_b64 s[38:39], s[22:23]
	v_mov_b32_e32 v77, v60
	s_nop 4
	v_fmac_f32_e32 v77, 0x3e000000, v16
	s_or_b64 exec, exec, s[38:39]
	s_and_saveexec_b64 s[38:39], s[24:25]
	v_mov_b32_e32 v76, v61
	v_fmac_f32_e32 v76, 0x3e000000, v17
	s_or_b64 exec, exec, s[38:39]
	v_mov_b32_e32 v78, 0xf149f2ca
	v_mov_b32_e32 v79, 0xf149f2ca
	s_and_saveexec_b64 s[38:39], s[26:27]
	v_mov_b32_e32 v79, v62
	v_fmac_f32_e32 v79, 0x3e000000, v18
	s_or_b64 exec, exec, s[38:39]
	s_and_saveexec_b64 s[38:39], s[28:29]
	v_mov_b32_e32 v78, v63
	v_fmac_f32_e32 v78, 0x3e000000, v19
	s_or_b64 exec, exec, s[38:39]
	s_waitcnt vmcnt(1)
	v_mfma_f32_16x16x32_bf16 v[12:15], v[12:15], v[4:7], 0
	v_mov_b32_e32 v80, 0xf149f2ca
	v_mov_b32_e32 v81, 0xf149f2ca
	s_waitcnt vmcnt(0)
	v_mfma_f32_16x16x32_bf16 v[8:11], v[8:11], v[0:3], v[12:15]
	s_and_saveexec_b64 s[38:39], s[30:31]
	v_mov_b32_e32 v81, v64
	s_nop 5
	v_fmac_f32_e32 v81, 0x3e000000, v8
	s_or_b64 exec, exec, s[38:39]
	s_and_saveexec_b64 s[38:39], s[34:35]
	v_mov_b32_e32 v80, v65
	v_fmac_f32_e32 v80, 0x3e000000, v9
	s_or_b64 exec, exec, s[38:39]
	v_mov_b32_e32 v82, 0xf149f2ca
	v_mov_b32_e32 v83, 0xf149f2ca
	s_and_saveexec_b64 s[38:39], s[36:37]
	v_mov_b32_e32 v83, v66
	v_fmac_f32_e32 v83, 0x3e000000, v10
	s_or_b64 exec, exec, s[38:39]
	s_and_saveexec_b64 s[38:39], s[6:7]
	v_mov_b32_e32 v82, v67
	v_fmac_f32_e32 v82, 0x3e000000, v11
	s_or_b64 exec, exec, s[38:39]
	s_add_i32 s38, s12, 0x80
	s_mov_b32 s39, s13
	v_lshl_add_u64 v[8:9], v[36:37], 0, s[38:39]
	v_lshlrev_b64 v[8:9], 11, v[8:9]
	v_lshl_add_u64 v[12:13], v[130:131], 0, v[8:9]
	global_load_dwordx4 v[8:11], v[12:13], off
	global_load_dwordx4 v[32:35], v[12:13], off offset:64
	s_add_i32 s38, s12, 0xc0
	v_lshl_add_u64 v[14:15], v[36:37], 0, s[38:39]
	v_lshlrev_b64 v[14:15], 11, v[14:15]
	v_add_co_u32_e32 v12, vcc, 0x2000, v12
	v_lshl_add_u64 v[14:15], v[130:131], 0, v[14:15]
	s_nop 0
	v_addc_co_u32_e32 v13, vcc, 0, v13, vcc
	v_add_co_u32_e32 v50, vcc, 0x2000, v14
	global_load_dwordx4 v[20:23], v[14:15], off
	global_load_dwordx4 v[16:19], v[14:15], off offset:64
	v_addc_co_u32_e32 v51, vcc, 0, v15, vcc
	global_load_dwordx4 v[28:31], v[12:13], off
	global_load_dwordx4 v[24:27], v[12:13], off offset:64
	v_mov_b32_e32 v84, 0xf149f2ca
	v_mov_b32_e32 v85, 0xf149f2ca
	s_waitcnt vmcnt(5)
	v_mfma_f32_16x16x32_bf16 v[46:49], v[8:11], v[4:7], 0
	global_load_dwordx4 v[12:15], v[50:51], off
	global_load_dwordx4 v[8:11], v[50:51], off offset:64
	s_waitcnt vmcnt(6)
; __device__ __forceinline__ f32x4 mfma16(bf16x8 a, bf16x8 b, f32x4 c) { return __builtin_amdgcn_mfma_f32_16x16x32_bf16(a, b, c, 0, 0, 0); }
; __device__ __forceinline__ void phase_attn(const Args& a, unsigned char* smem, int tid, int lane, int wave, bf16_t* Yout) {
;     ...
; #pragma unroll
;             for (int bt = 0; bt < 4; ++bt) {
;                 ATT_KLOAD(bt, 0);
;                 asm volatile("" ::: "memory");
; #pragma unroll
;                 for (int ii = 0; ii < 2; ++ii) {
;                     const int i = bt * 2 + ii;
;                     const float* rp = rpb_s + (rs + i - r + 7) * 31;
; #pragma unroll
;                     for (int hf = 0; hf < 2; ++hf) {
;                         f32x4 s = {0.f, 0.f, 0.f, 0.f};
;                         s = mfma16(kbuf[0][(ii * 2 + hf) * 2], qf0, s); s = mfma16(kbuf[0][(ii * 2 + hf) * 2 + 1], qf1, s);
; #pragma unroll
;                         for (int e = 0; e < 4; ++e) { const int kc = kc0 + 8 * g + 4 * hf + e; const bool ok = (kc >= cs) && (kc < cs + 16);
;                             const int dc = min(max(kc - qc + 15, 0), 30);
;                             s[e] = ok ? s[e] * 0.125f + rp[dc] : -1e30f; }
;                         st[i * 2 + hf] = s;
	v_mfma_f32_16x16x32_bf16 v[32:35], v[32:35], v[0:3], v[46:49]
	s_and_saveexec_b64 s[38:39], s[22:23]
	v_mov_b32_e32 v85, v184
	s_nop 5
	v_fmac_f32_e32 v85, 0x3e000000, v32
	s_or_b64 exec, exec, s[38:39]
	s_and_saveexec_b64 s[38:39], s[24:25]
	v_mov_b32_e32 v84, v185
	v_fmac_f32_e32 v84, 0x3e000000, v33
	s_or_b64 exec, exec, s[38:39]
	v_mov_b32_e32 v86, 0xf149f2ca
	v_mov_b32_e32 v87, 0xf149f2ca
	s_and_saveexec_b64 s[38:39], s[26:27]
	v_mov_b32_e32 v87, v186
	v_fmac_f32_e32 v87, 0x3e000000, v34
	s_or_b64 exec, exec, s[38:39]
	s_and_saveexec_b64 s[38:39], s[28:29]
	v_mov_b32_e32 v86, v187
	v_fmac_f32_e32 v86, 0x3e000000, v35
	s_or_b64 exec, exec, s[38:39]
	s_waitcnt vmcnt(3)
	v_mfma_f32_16x16x32_bf16 v[28:31], v[28:31], v[4:7], 0
	v_mov_b32_e32 v88, 0xf149f2ca
	v_mov_b32_e32 v89, 0xf149f2ca
	s_waitcnt vmcnt(2)
	v_mfma_f32_16x16x32_bf16 v[24:27], v[24:27], v[0:3], v[28:31]
	s_and_saveexec_b64 s[38:39], s[30:31]
	v_mov_b32_e32 v89, v188
	s_nop 5
	v_fmac_f32_e32 v89, 0x3e000000, v24
	s_or_b64 exec, exec, s[38:39]
	s_and_saveexec_b64 s[38:39], s[34:35]
	v_mov_b32_e32 v88, v189
	v_fmac_f32_e32 v88, 0x3e000000, v25
	s_or_b64 exec, exec, s[38:39]
	v_mov_b32_e32 v90, 0xf149f2ca
	v_mov_b32_e32 v91, 0xf149f2ca
	s_and_saveexec_b64 s[38:39], s[36:37]
	v_mov_b32_e32 v91, v190
	v_fmac_f32_e32 v91, 0x3e000000, v26
	s_or_b64 exec, exec, s[38:39]
	s_and_saveexec_b64 s[38:39], s[6:7]
	v_mov_b32_e32 v90, v191
	v_fmac_f32_e32 v90, 0x3e000000, v27
	s_or_b64 exec, exec, s[38:39]
	v_mfma_f32_16x16x32_bf16 v[20:23], v[20:23], v[4:7], 0
	v_mov_b32_e32 v92, 0xf149f2ca
	v_mov_b32_e32 v93, 0xf149f2ca
	v_mfma_f32_16x16x32_bf16 v[16:19], v[16:19], v[0:3], v[20:23]
	s_and_saveexec_b64 s[38:39], s[22:23]
	v_mov_b32_e32 v93, v192
	s_nop 5
	v_fmac_f32_e32 v93, 0x3e000000, v16
	s_or_b64 exec, exec, s[38:39]
	s_and_saveexec_b64 s[38:39], s[24:25]
	v_mov_b32_e32 v92, v193
	v_fmac_f32_e32 v92, 0x3e000000, v17
	s_or_b64 exec, exec, s[38:39]
	v_mov_b32_e32 v94, 0xf149f2ca
	v_mov_b32_e32 v95, 0xf149f2ca
	s_and_saveexec_b64 s[38:39], s[26:27]
	v_mov_b32_e32 v95, v194
	v_fmac_f32_e32 v95, 0x3e000000, v18
	s_or_b64 exec, exec, s[38:39]
	s_and_saveexec_b64 s[38:39], s[28:29]
	v_mov_b32_e32 v94, v195
	v_fmac_f32_e32 v94, 0x3e000000, v19
	s_or_b64 exec, exec, s[38:39]
	s_waitcnt vmcnt(1)
	v_mfma_f32_16x16x32_bf16 v[12:15], v[12:15], v[4:7], 0
	v_mov_b32_e32 v96, 0xf149f2ca
	v_mov_b32_e32 v97, 0xf149f2ca
	s_waitcnt vmcnt(0)
	v_mfma_f32_16x16x32_bf16 v[8:11], v[8:11], v[0:3], v[12:15]
	s_and_saveexec_b64 s[38:39], s[30:31]
	v_mov_b32_e32 v97, v196
	s_nop 5
	v_fmac_f32_e32 v97, 0x3e000000, v8
	s_or_b64 exec, exec, s[38:39]
	s_and_saveexec_b64 s[38:39], s[34:35]
	v_mov_b32_e32 v96, v197
	v_fmac_f32_e32 v96, 0x3e000000, v9
	s_or_b64 exec, exec, s[38:39]
	v_mov_b32_e32 v98, 0xf149f2ca
	v_mov_b32_e32 v99, 0xf149f2ca
	s_and_saveexec_b64 s[38:39], s[36:37]
	v_mov_b32_e32 v99, v198
	v_fmac_f32_e32 v99, 0x3e000000, v10
	s_or_b64 exec, exec, s[38:39]
	s_and_saveexec_b64 s[38:39], s[6:7]
	v_mov_b32_e32 v98, v199
	v_fmac_f32_e32 v98, 0x3e000000, v11
	s_or_b64 exec, exec, s[38:39]
	s_add_i32 s38, s12, 0x100
	s_mov_b32 s39, s13
	v_lshl_add_u64 v[8:9], v[36:37], 0, s[38:39]
	v_lshlrev_b64 v[8:9], 11, v[8:9]
	v_lshl_add_u64 v[12:13], v[130:131], 0, v[8:9]
	global_load_dwordx4 v[8:11], v[12:13], off
	global_load_dwordx4 v[32:35], v[12:13], off offset:64
	s_add_i32 s38, s12, 0x140
	v_lshl_add_u64 v[14:15], v[36:37], 0, s[38:39]
	v_lshlrev_b64 v[14:15], 11, v[14:15]
	v_add_co_u32_e32 v12, vcc, 0x2000, v12
	v_lshl_add_u64 v[14:15], v[130:131], 0, v[14:15]
	s_nop 0
	v_addc_co_u32_e32 v13, vcc, 0, v13, vcc
	v_add_co_u32_e32 v50, vcc, 0x2000, v14
	global_load_dwordx4 v[20:23], v[14:15], off
	global_load_dwordx4 v[16:19], v[14:15], off offset:64
	v_addc_co_u32_e32 v51, vcc, 0, v15, vcc
	global_load_dwordx4 v[28:31], v[12:13], off
	global_load_dwordx4 v[24:27], v[12:13], off offset:64
	v_mov_b32_e32 v100, 0xf149f2ca
	v_mov_b32_e32 v101, 0xf149f2ca
	s_waitcnt vmcnt(5)
	v_mfma_f32_16x16x32_bf16 v[46:49], v[8:11], v[4:7], 0
	global_load_dwordx4 v[12:15], v[50:51], off
	global_load_dwordx4 v[8:11], v[50:51], off offset:64
	s_waitcnt vmcnt(6)
	v_mfma_f32_16x16x32_bf16 v[32:35], v[32:35], v[0:3], v[46:49]
	s_and_saveexec_b64 s[38:39], s[22:23]
	v_mov_b32_e32 v101, v200
	s_nop 5
	v_fmac_f32_e32 v101, 0x3e000000, v32
	s_or_b64 exec, exec, s[38:39]
	s_and_saveexec_b64 s[38:39], s[24:25]
	v_mov_b32_e32 v100, v201
	v_fmac_f32_e32 v100, 0x3e000000, v33
	s_or_b64 exec, exec, s[38:39]
	v_mov_b32_e32 v102, 0xf149f2ca
	v_mov_b32_e32 v103, 0xf149f2ca
	s_and_saveexec_b64 s[38:39], s[26:27]
	v_mov_b32_e32 v103, v202
	v_fmac_f32_e32 v103, 0x3e000000, v34
	s_or_b64 exec, exec, s[38:39]
	s_and_saveexec_b64 s[38:39], s[28:29]
	v_mov_b32_e32 v102, v203
	v_fmac_f32_e32 v102, 0x3e000000, v35
	s_or_b64 exec, exec, s[38:39]
	s_waitcnt vmcnt(3)
	v_mfma_f32_16x16x32_bf16 v[28:31], v[28:31], v[4:7], 0
	v_mov_b32_e32 v104, 0xf149f2ca
	v_mov_b32_e32 v105, 0xf149f2ca
	s_waitcnt vmcnt(2)
; __device__ __forceinline__ f32x4 mfma16(bf16x8 a, bf16x8 b, f32x4 c) { return __builtin_amdgcn_mfma_f32_16x16x32_bf16(a, b, c, 0, 0, 0); }
; __device__ __forceinline__ void phase_attn(const Args& a, unsigned char* smem, int tid, int lane, int wave, bf16_t* Yout) {
;     ...
; #pragma unroll
;             for (int bt = 0; bt < 4; ++bt) {
;                 ATT_KLOAD(bt, 0);
;                 asm volatile("" ::: "memory");
; #pragma unroll
;                 for (int ii = 0; ii < 2; ++ii) {
;                     const int i = bt * 2 + ii;
;                     const float* rp = rpb_s + (rs + i - r + 7) * 31;
; #pragma unroll
;                     for (int hf = 0; hf < 2; ++hf) {
;                         f32x4 s = {0.f, 0.f, 0.f, 0.f};
;                         s = mfma16(kbuf[0][(ii * 2 + hf) * 2], qf0, s); s = mfma16(kbuf[0][(ii * 2 + hf) * 2 + 1], qf1, s);
; #pragma unroll
;                         for (int e = 0; e < 4; ++e) { const int kc = kc0 + 8 * g + 4 * hf + e; const bool ok = (kc >= cs) && (kc < cs + 16);
;                             const int dc = min(max(kc - qc + 15, 0), 30);
;                             s[e] = ok ? s[e] * 0.125f + rp[dc] : -1e30f; }
;                         st[i * 2 + hf] = s;
	v_mfma_f32_16x16x32_bf16 v[24:27], v[24:27], v[0:3], v[28:31]
	s_and_saveexec_b64 s[38:39], s[30:31]
	v_mov_b32_e32 v105, v204
	s_nop 5
	v_fmac_f32_e32 v105, 0x3e000000, v24
	s_or_b64 exec, exec, s[38:39]
	s_and_saveexec_b64 s[38:39], s[34:35]
	v_mov_b32_e32 v104, v205
	v_fmac_f32_e32 v104, 0x3e000000, v25
	s_or_b64 exec, exec, s[38:39]
	v_mov_b32_e32 v106, 0xf149f2ca
	v_mov_b32_e32 v107, 0xf149f2ca
	s_and_saveexec_b64 s[38:39], s[36:37]
	v_mov_b32_e32 v107, v206
	v_fmac_f32_e32 v107, 0x3e000000, v26
	s_or_b64 exec, exec, s[38:39]
	s_and_saveexec_b64 s[38:39], s[6:7]
	v_mov_b32_e32 v106, v207
	v_fmac_f32_e32 v106, 0x3e000000, v27
	s_or_b64 exec, exec, s[38:39]
	v_mfma_f32_16x16x32_bf16 v[20:23], v[20:23], v[4:7], 0
	v_mov_b32_e32 v108, 0xf149f2ca
	v_mov_b32_e32 v109, 0xf149f2ca
	v_mfma_f32_16x16x32_bf16 v[16:19], v[16:19], v[0:3], v[20:23]
	s_and_saveexec_b64 s[38:39], s[22:23]
	v_mov_b32_e32 v109, v208
	s_nop 5
	v_fmac_f32_e32 v109, 0x3e000000, v16
	s_or_b64 exec, exec, s[38:39]
	s_and_saveexec_b64 s[38:39], s[24:25]
	v_mov_b32_e32 v108, v209
	v_fmac_f32_e32 v108, 0x3e000000, v17
	s_or_b64 exec, exec, s[38:39]
	v_mov_b32_e32 v110, 0xf149f2ca
	v_mov_b32_e32 v111, 0xf149f2ca
	s_and_saveexec_b64 s[38:39], s[26:27]
	v_mov_b32_e32 v111, v210
	v_fmac_f32_e32 v111, 0x3e000000, v18
	s_or_b64 exec, exec, s[38:39]
	s_and_saveexec_b64 s[38:39], s[28:29]
	v_mov_b32_e32 v110, v211
	v_fmac_f32_e32 v110, 0x3e000000, v19
	s_or_b64 exec, exec, s[38:39]
	s_waitcnt vmcnt(1)
	v_mfma_f32_16x16x32_bf16 v[12:15], v[12:15], v[4:7], 0
	v_mov_b32_e32 v147, 0xf149f2ca
	v_mov_b32_e32 v148, 0xf149f2ca
	s_waitcnt vmcnt(0)
	v_mfma_f32_16x16x32_bf16 v[8:11], v[8:11], v[0:3], v[12:15]
	s_and_saveexec_b64 s[38:39], s[30:31]
	v_mov_b32_e32 v148, v212
	s_nop 5
	v_fmac_f32_e32 v148, 0x3e000000, v8
	s_or_b64 exec, exec, s[38:39]
	s_and_saveexec_b64 s[38:39], s[34:35]
	v_mov_b32_e32 v147, v213
	v_fmac_f32_e32 v147, 0x3e000000, v9
	s_or_b64 exec, exec, s[38:39]
	v_mov_b32_e32 v149, 0xf149f2ca
	v_mov_b32_e32 v150, 0xf149f2ca
	s_and_saveexec_b64 s[38:39], s[36:37]
	v_mov_b32_e32 v150, v214
	v_fmac_f32_e32 v150, 0x3e000000, v10
	s_or_b64 exec, exec, s[38:39]
	s_and_saveexec_b64 s[38:39], s[6:7]
	v_mov_b32_e32 v149, v215
	v_fmac_f32_e32 v149, 0x3e000000, v11
	s_or_b64 exec, exec, s[38:39]
	s_add_i32 s38, s12, 0x180
	s_mov_b32 s39, s13
	v_lshl_add_u64 v[8:9], v[36:37], 0, s[38:39]
	v_lshlrev_b64 v[8:9], 11, v[8:9]
	v_lshl_add_u64 v[12:13], v[130:131], 0, v[8:9]
	global_load_dwordx4 v[8:11], v[12:13], off
	global_load_dwordx4 v[32:35], v[12:13], off offset:64
	s_add_i32 s38, s12, 0x1c0
	v_lshl_add_u64 v[14:15], v[36:37], 0, s[38:39]
	v_lshlrev_b64 v[14:15], 11, v[14:15]
	v_add_co_u32_e32 v12, vcc, 0x2000, v12
	v_lshl_add_u64 v[14:15], v[130:131], 0, v[14:15]
	s_nop 0
	v_addc_co_u32_e32 v13, vcc, 0, v13, vcc
	v_add_co_u32_e32 v36, vcc, 0x2000, v14
	global_load_dwordx4 v[20:23], v[14:15], off
	global_load_dwordx4 v[16:19], v[14:15], off offset:64
	v_addc_co_u32_e32 v37, vcc, 0, v15, vcc
	global_load_dwordx4 v[28:31], v[12:13], off
	global_load_dwordx4 v[24:27], v[12:13], off offset:64
	v_mov_b32_e32 v151, 0xf149f2ca
	v_mov_b32_e32 v152, 0xf149f2ca
	s_waitcnt vmcnt(5)
	v_mfma_f32_16x16x32_bf16 v[46:49], v[8:11], v[4:7], 0
	global_load_dwordx4 v[12:15], v[36:37], off
	global_load_dwordx4 v[8:11], v[36:37], off offset:64
	s_waitcnt vmcnt(6)
	v_mfma_f32_16x16x32_bf16 v[32:35], v[32:35], v[0:3], v[46:49]
	s_and_saveexec_b64 s[38:39], s[22:23]
	v_mov_b32_e32 v152, v227
	s_nop 5
	v_fmac_f32_e32 v152, 0x3e000000, v32
	s_or_b64 exec, exec, s[38:39]
	s_and_saveexec_b64 s[38:39], s[24:25]
	v_mov_b32_e32 v151, v228
	v_fmac_f32_e32 v151, 0x3e000000, v33
	s_or_b64 exec, exec, s[38:39]
	v_mov_b32_e32 v153, 0xf149f2ca
	v_mov_b32_e32 v154, 0xf149f2ca
	s_and_saveexec_b64 s[38:39], s[26:27]
	v_mov_b32_e32 v154, v229
	v_fmac_f32_e32 v154, 0x3e000000, v34
	s_or_b64 exec, exec, s[38:39]
	s_and_saveexec_b64 s[38:39], s[28:29]
	v_mov_b32_e32 v153, v230
	v_fmac_f32_e32 v153, 0x3e000000, v35
	s_or_b64 exec, exec, s[38:39]
	s_waitcnt vmcnt(3)
	v_mfma_f32_16x16x32_bf16 v[28:31], v[28:31], v[4:7], 0
	v_mov_b32_e32 v155, 0xf149f2ca
	v_mov_b32_e32 v216, 0xf149f2ca
	s_waitcnt vmcnt(2)
	v_mfma_f32_16x16x32_bf16 v[24:27], v[24:27], v[0:3], v[28:31]
	s_and_saveexec_b64 s[38:39], s[30:31]
	v_mov_b32_e32 v216, v231
	s_nop 5
	v_fmac_f32_e32 v216, 0x3e000000, v24
	s_or_b64 exec, exec, s[38:39]
	s_and_saveexec_b64 s[38:39], s[34:35]
	v_mov_b32_e32 v155, v232
	v_fmac_f32_e32 v155, 0x3e000000, v25
	s_or_b64 exec, exec, s[38:39]
	v_mov_b32_e32 v217, 0xf149f2ca
	v_mov_b32_e32 v218, 0xf149f2ca
	s_and_saveexec_b64 s[38:39], s[36:37]
	v_mov_b32_e32 v218, v233
	v_fmac_f32_e32 v218, 0x3e000000, v26
	s_or_b64 exec, exec, s[38:39]
	s_and_saveexec_b64 s[38:39], s[6:7]
	v_mov_b32_e32 v217, v234
	v_fmac_f32_e32 v217, 0x3e000000, v27
	s_or_b64 exec, exec, s[38:39]
	v_mfma_f32_16x16x32_bf16 v[20:23], v[20:23], v[4:7], 0
	v_mov_b32_e32 v219, 0xf149f2ca
	v_mov_b32_e32 v220, 0xf149f2ca
	v_mfma_f32_16x16x32_bf16 v[16:19], v[16:19], v[0:3], v[20:23]
	s_and_saveexec_b64 s[38:39], s[22:23]
	v_mov_b32_e32 v220, v235
	s_nop 5
	v_fmac_f32_e32 v220, 0x3e000000, v16
	s_or_b64 exec, exec, s[38:39]
	s_and_saveexec_b64 s[22:23], s[24:25]
	v_mov_b32_e32 v219, v236
	v_fmac_f32_e32 v219, 0x3e000000, v17
	s_or_b64 exec, exec, s[22:23]
	v_mov_b32_e32 v221, 0xf149f2ca
	v_mov_b32_e32 v222, 0xf149f2ca
	s_and_saveexec_b64 s[22:23], s[26:27]
	v_mov_b32_e32 v222, v237
	v_fmac_f32_e32 v222, 0x3e000000, v18
	s_or_b64 exec, exec, s[22:23]
	s_and_saveexec_b64 s[22:23], s[28:29]
	v_mov_b32_e32 v221, v238
	v_fmac_f32_e32 v221, 0x3e000000, v19
	s_or_b64 exec, exec, s[22:23]
	s_waitcnt vmcnt(1)
	v_mfma_f32_16x16x32_bf16 v[12:15], v[12:15], v[4:7], 0
	v_mov_b32_e32 v223, 0xf149f2ca
	v_mov_b32_e32 v224, 0xf149f2ca
	s_waitcnt vmcnt(0)
	v_mfma_f32_16x16x32_bf16 v[8:11], v[8:11], v[0:3], v[12:15]
	s_and_saveexec_b64 s[22:23], s[30:31]
	v_mov_b32_e32 v224, v239
	s_nop 5
	v_fmac_f32_e32 v224, 0x3e000000, v8
	s_or_b64 exec, exec, s[22:23]
	s_and_saveexec_b64 s[22:23], s[34:35]
	v_mov_b32_e32 v223, v240
	v_fmac_f32_e32 v223, 0x3e000000, v9
	s_or_b64 exec, exec, s[22:23]
	v_mov_b32_e32 v225, 0xf149f2ca
	v_mov_b32_e32 v226, 0xf149f2ca
	s_and_saveexec_b64 s[22:23], s[36:37]
	v_mov_b32_e32 v226, v241
	v_fmac_f32_e32 v226, 0x3e000000, v10
	s_or_b64 exec, exec, s[22:23]
	s_and_saveexec_b64 s[22:23], s[6:7]
	s_cbranch_execz .LBB0_334
	v_add_u32_e32 v8, 15, v45
	v_min_u32_e32 v8, 30, v8
	v_lshl_add_u32 v8, v8, 2, s1
	ds_read_b32 v225, v8 offset:1736
	s_waitcnt lgkmcnt(0)
	v_fmac_f32_e32 v225, 0x3e000000, v11
	s_branch .LBB0_334
